# v31 + P5 sample-row thin GEMM K-loop software-pipelined: fully unrolled, two register sets, next 4-k-step group's loads in flight before the current MFMAs (was: 20 loads, drain, loop)
# baseline (speedup 1.0000x reference)
.LBB0_724:
	v_lshl_add_u64 v[192:193], v[20:21], 0, s[6:7]
	v_lshl_add_u64 v[194:195], v[18:19], 0, s[6:7]
	s_mov_b64 s[98:99], 0x2f20000
	s_mov_b64 s[100:101], 0x2f40000
	v_lshl_add_u64 v[196:197], v[194:195], 0, s[98:99]
	v_lshl_add_u64 v[198:199], v[194:195], 0, s[100:101]
	s_mov_b64 s[98:99], 0x2f60000
	s_mov_b64 s[100:101], 0x2f00000
	v_lshl_add_u64 v[200:201], v[194:195], 0, s[98:99]
	v_lshl_add_u64 v[194:195], v[194:195], 0, s[100:101]
	global_load_dwordx4 v[24:27], v[192:193], off offset:-128
	global_load_dwordx4 v[40:43], v[194:195], off
	global_load_dwordx4 v[56:59], v[196:197], off
	global_load_dwordx4 v[72:75], v[198:199], off
	global_load_dwordx4 v[88:91], v[200:201], off
	global_load_dwordx4 v[28:31], v[192:193], off offset:-64
	global_load_dwordx4 v[44:47], v[194:195], off offset:64
	global_load_dwordx4 v[60:63], v[196:197], off offset:64
	global_load_dwordx4 v[76:79], v[198:199], off offset:64
	global_load_dwordx4 v[92:95], v[200:201], off offset:64
	global_load_dwordx4 v[32:35], v[192:193], off
	global_load_dwordx4 v[48:51], v[194:195], off offset:128
	global_load_dwordx4 v[64:67], v[196:197], off offset:128
	global_load_dwordx4 v[80:83], v[198:199], off offset:128
	global_load_dwordx4 v[96:99], v[200:201], off offset:128
	global_load_dwordx4 v[36:39], v[192:193], off offset:64
	global_load_dwordx4 v[52:55], v[194:195], off offset:192
	global_load_dwordx4 v[68:71], v[196:197], off offset:192
	global_load_dwordx4 v[84:87], v[198:199], off offset:192
	global_load_dwordx4 v[100:103], v[200:201], off offset:192
	global_load_dwordx4 v[104:107], v[192:193], off offset:128
	global_load_dwordx4 v[120:123], v[194:195], off offset:256
	global_load_dwordx4 v[136:139], v[196:197], off offset:256
	global_load_dwordx4 v[152:155], v[198:199], off offset:256
	global_load_dwordx4 v[168:171], v[200:201], off offset:256
	global_load_dwordx4 v[108:111], v[192:193], off offset:192
	global_load_dwordx4 v[124:127], v[194:195], off offset:320
	global_load_dwordx4 v[140:143], v[196:197], off offset:320
	global_load_dwordx4 v[156:159], v[198:199], off offset:320
	global_load_dwordx4 v[172:175], v[200:201], off offset:320
	global_load_dwordx4 v[112:115], v[192:193], off offset:256
	global_load_dwordx4 v[128:131], v[194:195], off offset:384
	global_load_dwordx4 v[144:147], v[196:197], off offset:384
	global_load_dwordx4 v[160:163], v[198:199], off offset:384
	global_load_dwordx4 v[176:179], v[200:201], off offset:384
	global_load_dwordx4 v[116:119], v[192:193], off offset:320
	global_load_dwordx4 v[132:135], v[194:195], off offset:448
	global_load_dwordx4 v[148:151], v[196:197], off offset:448
	global_load_dwordx4 v[164:167], v[198:199], off offset:448
	global_load_dwordx4 v[180:183], v[200:201], off offset:448
	s_waitcnt vmcnt(38)
	v_mfma_f32_16x16x32_bf16 v[6:9], v[24:27], v[40:43], v[6:9]
	global_load_dwordx4 v[40:43], v[194:195], off offset:512
	s_waitcnt vmcnt(38)
	v_mfma_f32_16x16x32_bf16 v[10:13], v[24:27], v[56:59], v[10:13]
	global_load_dwordx4 v[56:59], v[196:197], off offset:512
	s_waitcnt vmcnt(38)
	v_mfma_f32_16x16x32_bf16 v[14:17], v[24:27], v[72:75], v[14:17]
	global_load_dwordx4 v[72:75], v[198:199], off offset:512
	s_waitcnt vmcnt(38)
	v_mfma_f32_16x16x32_bf16 v[2:5], v[24:27], v[88:91], v[2:5]
	global_load_dwordx4 v[88:91], v[200:201], off offset:512
	global_load_dwordx4 v[24:27], v[192:193], off offset:384
	s_waitcnt vmcnt(38)
	v_mfma_f32_16x16x32_bf16 v[6:9], v[28:31], v[44:47], v[6:9]
	global_load_dwordx4 v[44:47], v[194:195], off offset:576
	s_waitcnt vmcnt(38)
	v_mfma_f32_16x16x32_bf16 v[10:13], v[28:31], v[60:63], v[10:13]
	global_load_dwordx4 v[60:63], v[196:197], off offset:576
	s_waitcnt vmcnt(38)
	v_mfma_f32_16x16x32_bf16 v[14:17], v[28:31], v[76:79], v[14:17]
	global_load_dwordx4 v[76:79], v[198:199], off offset:576
	s_waitcnt vmcnt(38)
	v_mfma_f32_16x16x32_bf16 v[2:5], v[28:31], v[92:95], v[2:5]
	global_load_dwordx4 v[92:95], v[200:201], off offset:576
	global_load_dwordx4 v[28:31], v[192:193], off offset:448
	s_waitcnt vmcnt(38)
	v_mfma_f32_16x16x32_bf16 v[6:9], v[32:35], v[48:51], v[6:9]
	global_load_dwordx4 v[48:51], v[194:195], off offset:640
	s_waitcnt vmcnt(38)
	v_mfma_f32_16x16x32_bf16 v[10:13], v[32:35], v[64:67], v[10:13]
	global_load_dwordx4 v[64:67], v[196:197], off offset:640
	s_waitcnt vmcnt(38)
	v_mfma_f32_16x16x32_bf16 v[14:17], v[32:35], v[80:83], v[14:17]
	global_load_dwordx4 v[80:83], v[198:199], off offset:640
	s_waitcnt vmcnt(38)
	v_mfma_f32_16x16x32_bf16 v[2:5], v[32:35], v[96:99], v[2:5]
	global_load_dwordx4 v[96:99], v[200:201], off offset:640
	global_load_dwordx4 v[32:35], v[192:193], off offset:512
	s_waitcnt vmcnt(38)
	v_mfma_f32_16x16x32_bf16 v[6:9], v[36:39], v[52:55], v[6:9]
	global_load_dwordx4 v[52:55], v[194:195], off offset:704
	s_waitcnt vmcnt(38)
	v_mfma_f32_16x16x32_bf16 v[10:13], v[36:39], v[68:71], v[10:13]
	global_load_dwordx4 v[68:71], v[196:197], off offset:704
	s_waitcnt vmcnt(38)
	v_mfma_f32_16x16x32_bf16 v[14:17], v[36:39], v[84:87], v[14:17]
	global_load_dwordx4 v[84:87], v[198:199], off offset:704
	s_waitcnt vmcnt(38)
	v_mfma_f32_16x16x32_bf16 v[2:5], v[36:39], v[100:103], v[2:5]
	global_load_dwordx4 v[100:103], v[200:201], off offset:704
	global_load_dwordx4 v[36:39], v[192:193], off offset:576
	s_waitcnt vmcnt(38)
	v_mfma_f32_16x16x32_bf16 v[6:9], v[104:107], v[120:123], v[6:9]
	global_load_dwordx4 v[120:123], v[194:195], off offset:768
	s_waitcnt vmcnt(38)
	v_mfma_f32_16x16x32_bf16 v[10:13], v[104:107], v[136:139], v[10:13]
	global_load_dwordx4 v[136:139], v[196:197], off offset:768
	s_waitcnt vmcnt(38)
	v_mfma_f32_16x16x32_bf16 v[14:17], v[104:107], v[152:155], v[14:17]
	global_load_dwordx4 v[152:155], v[198:199], off offset:768
	s_waitcnt vmcnt(38)
	v_mfma_f32_16x16x32_bf16 v[2:5], v[104:107], v[168:171], v[2:5]
	global_load_dwordx4 v[168:171], v[200:201], off offset:768
	global_load_dwordx4 v[104:107], v[192:193], off offset:640
	s_waitcnt vmcnt(38)
	v_mfma_f32_16x16x32_bf16 v[6:9], v[108:111], v[124:127], v[6:9]
	global_load_dwordx4 v[124:127], v[194:195], off offset:832
	s_waitcnt vmcnt(38)
	v_mfma_f32_16x16x32_bf16 v[10:13], v[108:111], v[140:143], v[10:13]
	global_load_dwordx4 v[140:143], v[196:197], off offset:832
	s_waitcnt vmcnt(38)
	v_mfma_f32_16x16x32_bf16 v[14:17], v[108:111], v[156:159], v[14:17]
	global_load_dwordx4 v[156:159], v[198:199], off offset:832
	s_waitcnt vmcnt(38)
	v_mfma_f32_16x16x32_bf16 v[2:5], v[108:111], v[172:175], v[2:5]
	global_load_dwordx4 v[172:175], v[200:201], off offset:832
	global_load_dwordx4 v[108:111], v[192:193], off offset:704
	s_waitcnt vmcnt(38)
	v_mfma_f32_16x16x32_bf16 v[6:9], v[112:115], v[128:131], v[6:9]
	global_load_dwordx4 v[128:131], v[194:195], off offset:896
	s_waitcnt vmcnt(38)
	v_mfma_f32_16x16x32_bf16 v[10:13], v[112:115], v[144:147], v[10:13]
	global_load_dwordx4 v[144:147], v[196:197], off offset:896
	s_waitcnt vmcnt(38)
	v_mfma_f32_16x16x32_bf16 v[14:17], v[112:115], v[160:163], v[14:17]
	global_load_dwordx4 v[160:163], v[198:199], off offset:896
	s_waitcnt vmcnt(38)
	v_mfma_f32_16x16x32_bf16 v[2:5], v[112:115], v[176:179], v[2:5]
	global_load_dwordx4 v[176:179], v[200:201], off offset:896
	global_load_dwordx4 v[112:115], v[192:193], off offset:768
	s_waitcnt vmcnt(38)
	v_mfma_f32_16x16x32_bf16 v[6:9], v[116:119], v[132:135], v[6:9]
	global_load_dwordx4 v[132:135], v[194:195], off offset:960
	s_waitcnt vmcnt(38)
	v_mfma_f32_16x16x32_bf16 v[10:13], v[116:119], v[148:151], v[10:13]
	global_load_dwordx4 v[148:151], v[196:197], off offset:960
	s_waitcnt vmcnt(38)
	v_mfma_f32_16x16x32_bf16 v[14:17], v[116:119], v[164:167], v[14:17]
	global_load_dwordx4 v[164:167], v[198:199], off offset:960
	s_waitcnt vmcnt(38)
	v_mfma_f32_16x16x32_bf16 v[2:5], v[116:119], v[180:183], v[2:5]
	global_load_dwordx4 v[180:183], v[200:201], off offset:960
	global_load_dwordx4 v[116:119], v[192:193], off offset:832
	s_waitcnt vmcnt(35)
	v_mfma_f32_16x16x32_bf16 v[6:9], v[24:27], v[40:43], v[6:9]
	v_mfma_f32_16x16x32_bf16 v[10:13], v[24:27], v[56:59], v[10:13]
	v_mfma_f32_16x16x32_bf16 v[14:17], v[24:27], v[72:75], v[14:17]
	v_mfma_f32_16x16x32_bf16 v[2:5], v[24:27], v[88:91], v[2:5]
	s_waitcnt vmcnt(30)
	v_mfma_f32_16x16x32_bf16 v[6:9], v[28:31], v[44:47], v[6:9]
	v_mfma_f32_16x16x32_bf16 v[10:13], v[28:31], v[60:63], v[10:13]
	v_mfma_f32_16x16x32_bf16 v[14:17], v[28:31], v[76:79], v[14:17]
	v_mfma_f32_16x16x32_bf16 v[2:5], v[28:31], v[92:95], v[2:5]
	s_waitcnt vmcnt(25)
	v_mfma_f32_16x16x32_bf16 v[6:9], v[32:35], v[48:51], v[6:9]
	v_mfma_f32_16x16x32_bf16 v[10:13], v[32:35], v[64:67], v[10:13]
	v_mfma_f32_16x16x32_bf16 v[14:17], v[32:35], v[80:83], v[14:17]
	v_mfma_f32_16x16x32_bf16 v[2:5], v[32:35], v[96:99], v[2:5]
	s_waitcnt vmcnt(20)
	v_mfma_f32_16x16x32_bf16 v[6:9], v[36:39], v[52:55], v[6:9]
	v_mfma_f32_16x16x32_bf16 v[10:13], v[36:39], v[68:71], v[10:13]
	v_mfma_f32_16x16x32_bf16 v[14:17], v[36:39], v[84:87], v[14:17]
	v_mfma_f32_16x16x32_bf16 v[2:5], v[36:39], v[100:103], v[2:5]
	s_waitcnt vmcnt(15)
	v_mfma_f32_16x16x32_bf16 v[6:9], v[104:107], v[120:123], v[6:9]
	v_mfma_f32_16x16x32_bf16 v[10:13], v[104:107], v[136:139], v[10:13]
	v_mfma_f32_16x16x32_bf16 v[14:17], v[104:107], v[152:155], v[14:17]
	v_mfma_f32_16x16x32_bf16 v[2:5], v[104:107], v[168:171], v[2:5]
	s_waitcnt vmcnt(10)
	v_mfma_f32_16x16x32_bf16 v[6:9], v[108:111], v[124:127], v[6:9]
	v_mfma_f32_16x16x32_bf16 v[10:13], v[108:111], v[140:143], v[10:13]
	v_mfma_f32_16x16x32_bf16 v[14:17], v[108:111], v[156:159], v[14:17]
	v_mfma_f32_16x16x32_bf16 v[2:5], v[108:111], v[172:175], v[2:5]
	s_waitcnt vmcnt(5)
	v_mfma_f32_16x16x32_bf16 v[6:9], v[112:115], v[128:131], v[6:9]
	v_mfma_f32_16x16x32_bf16 v[10:13], v[112:115], v[144:147], v[10:13]
	v_mfma_f32_16x16x32_bf16 v[14:17], v[112:115], v[160:163], v[14:17]
	v_mfma_f32_16x16x32_bf16 v[2:5], v[112:115], v[176:179], v[2:5]
	s_waitcnt vmcnt(0)
	v_mfma_f32_16x16x32_bf16 v[6:9], v[116:119], v[132:135], v[6:9]
	v_mfma_f32_16x16x32_bf16 v[10:13], v[116:119], v[148:151], v[10:13]
	v_mfma_f32_16x16x32_bf16 v[14:17], v[116:119], v[164:167], v[14:17]
	v_mfma_f32_16x16x32_bf16 v[2:5], v[116:119], v[180:183], v[2:5]
	v_and_b32_e32 v18, 3, v22
	s_mulk_i32 s3, 0x1400
	s_add_i32 s3, s3, 0
	v_lshlrev_b32_e32 v18, 4, v18
	v_mul_u32_u24_e32 v19, 0x50, v189
	v_add3_u32 v18, s3, v18, v19
	s_movk_i32 s3, 0x80
	v_cmp_gt_u32_e32 vcc, s3, v0
	ds_write_b128 v18, v[6:9]
	ds_write_b128 v18, v[10:13] offset:1280
	ds_write_b128 v18, v[14:17] offset:2560
	ds_write_b128 v18, v[2:5] offset:3840
	s_waitcnt lgkmcnt(0)
	s_barrier
	s_and_saveexec_b64 s[6:7], vcc
	s_cbranch_execz .LBB0_728
	v_or_b32_e32 v2, s1, v187
	v_ashrrev_i32_e32 v3, 31, v2
	v_lshlrev_b64 v[4:5], 10, v[2:3]
	s_ashr_i32 s5, s4, 31
	v_and_b32_e32 v82, 1, v0
	v_lshl_add_u64 v[76:77], v[4:5], 0, s[4:5]
	v_lshl_or_b32 v76, v82, 3, v76
	v_readlane_b32 s36, v251, 6
	v_lshlrev_b64 v[78:79], 2, v[76:77]
	v_readlane_b32 s48, v251, 18
	v_readlane_b32 s49, v251, 19
	s_brev_b32 s1, 32
	s_mov_b64 s[4:5], 0x4000000
	v_lshl_add_u64 v[8:9], s[48:49], 0, v[78:79]
	v_add_co_u32_e32 v4, vcc, s1, v8
	v_mul_u32_u24_e32 v3, 0x50, v187
	s_nop 0
	v_addc_co_u32_e32 v5, vcc, 0, v9, vcc
	v_lshl_add_u64 v[8:9], v[8:9], 0, s[4:5]
	global_load_dwordx4 v[4:7], v[4:5], off
	v_lshlrev_b32_e32 v12, 5, v82
	global_load_dwordx4 v[8:11], v[8:9], off offset:16
	v_add3_u32 v3, 0, v3, v12
	ds_read_b128 v[12:15], v3
	ds_read_b128 v[16:19], v3 offset:16
	ds_read_b128 v[20:23], v3 offset:5120
	ds_read_b128 v[24:27], v3 offset:5136
	ds_read_b128 v[28:31], v3 offset:10240
	ds_read_b128 v[32:35], v3 offset:10256
	ds_read_b128 v[36:39], v3 offset:15360
	ds_read_b128 v[40:43], v3 offset:15376
	ds_read_b128 v[44:47], v3 offset:20480
	ds_read_b128 v[48:51], v3 offset:20496
	ds_read_b128 v[52:55], v3 offset:25600
	ds_read_b128 v[56:59], v3 offset:25616
	ds_read_b128 v[60:63], v3 offset:30720
	ds_read_b128 v[64:67], v3 offset:30736
	ds_read_b128 v[68:71], v3 offset:35840
	ds_read_b128 v[72:75], v3 offset:35856
	s_waitcnt lgkmcnt(14)
	v_pk_add_f32 v[12:13], v[12:13], 0 op_sel_hi:[1,0]
	v_pk_add_f32 v[14:15], v[14:15], 0 op_sel_hi:[1,0]
	v_pk_add_f32 v[16:17], v[16:17], 0 op_sel_hi:[1,0]
	v_pk_add_f32 v[18:19], v[18:19], 0 op_sel_hi:[1,0]
	s_waitcnt lgkmcnt(13)
	v_pk_add_f32 v[12:13], v[12:13], v[20:21]
	v_pk_add_f32 v[14:15], v[14:15], v[22:23]
	s_waitcnt lgkmcnt(12)
	v_pk_add_f32 v[16:17], v[16:17], v[24:25]
	v_pk_add_f32 v[18:19], v[18:19], v[26:27]
	s_waitcnt lgkmcnt(11)
	v_pk_add_f32 v[12:13], v[12:13], v[28:29]
	v_pk_add_f32 v[14:15], v[14:15], v[30:31]
	s_waitcnt lgkmcnt(10)
	v_pk_add_f32 v[16:17], v[16:17], v[32:33]
	v_pk_add_f32 v[18:19], v[18:19], v[34:35]
	s_waitcnt lgkmcnt(9)
	v_pk_add_f32 v[12:13], v[12:13], v[36:37]
	v_pk_add_f32 v[14:15], v[14:15], v[38:39]
	s_waitcnt lgkmcnt(8)
	v_pk_add_f32 v[16:17], v[16:17], v[40:41]
	v_pk_add_f32 v[18:19], v[18:19], v[42:43]
	s_waitcnt lgkmcnt(7)
	v_pk_add_f32 v[12:13], v[12:13], v[44:45]
	v_pk_add_f32 v[14:15], v[14:15], v[46:47]
	s_waitcnt lgkmcnt(6)
	v_pk_add_f32 v[16:17], v[16:17], v[48:49]
	v_pk_add_f32 v[18:19], v[18:19], v[50:51]
	s_waitcnt lgkmcnt(5)
	v_pk_add_f32 v[12:13], v[12:13], v[52:53]
	v_pk_add_f32 v[14:15], v[14:15], v[54:55]
	s_waitcnt lgkmcnt(4)
	v_pk_add_f32 v[16:17], v[16:17], v[56:57]
	v_pk_add_f32 v[18:19], v[18:19], v[58:59]
	s_waitcnt lgkmcnt(3)
	v_pk_add_f32 v[12:13], v[12:13], v[60:61]
	v_pk_add_f32 v[14:15], v[14:15], v[62:63]
	s_waitcnt lgkmcnt(2)
	v_pk_add_f32 v[16:17], v[16:17], v[64:65]
	v_pk_add_f32 v[18:19], v[18:19], v[66:67]
	s_waitcnt lgkmcnt(1)
	v_pk_add_f32 v[12:13], v[12:13], v[68:69]
	v_pk_add_f32 v[14:15], v[14:15], v[70:71]
	s_waitcnt lgkmcnt(0)
	v_pk_add_f32 v[16:17], v[16:17], v[72:73]
	v_pk_add_f32 v[18:19], v[18:19], v[74:75]
	s_movk_i32 s1, 0x7fff
	v_lshl_add_u64 v[78:79], s[10:11], 0, v[78:79]
	v_lshl_add_u64 v[80:81], v[78:79], 0, 16
	v_lshl_add_u64 v[76:77], v[76:77], 1, s[14:15]
	v_cmp_eq_u32_e32 vcc, 0, v82
	v_readlane_b32 s37, v251, 7
	v_readlane_b32 s38, v251, 8
	v_readlane_b32 s39, v251, 9
	v_readlane_b32 s40, v251, 10
	v_readlane_b32 s41, v251, 11
	v_readlane_b32 s42, v251, 12
	v_readlane_b32 s43, v251, 13
	v_readlane_b32 s44, v251, 14
	v_readlane_b32 s45, v251, 15
	v_readlane_b32 s46, v251, 16
	v_readlane_b32 s47, v251, 17
	v_readlane_b32 s50, v251, 20
	v_readlane_b32 s51, v251, 21
	s_waitcnt vmcnt(1)
	v_pk_add_f32 v[4:5], v[12:13], v[4:5]
	v_pk_add_f32 v[6:7], v[14:15], v[6:7]
	s_waitcnt vmcnt(0)
	v_pk_add_f32 v[8:9], v[16:17], v[8:9]
	v_pk_add_f32 v[10:11], v[18:19], v[10:11]
	v_bfe_u32 v13, v9, 16, 1
	v_bfe_u32 v14, v5, 16, 1
	v_bfe_u32 v15, v6, 16, 1
	v_bfe_u32 v16, v10, 16, 1
	v_bfe_u32 v3, v11, 16, 1
	v_bfe_u32 v12, v7, 16, 1
	v_bfe_u32 v17, v4, 16, 1
	v_add3_u32 v18, v5, v14, s1
	v_add3_u32 v14, v9, v13, s1
	v_bfe_u32 v13, v8, 16, 1
	v_add3_u32 v16, v10, v16, s1
	v_add3_u32 v15, v6, v15, s1
	global_store_dwordx4 v[78:79], v[4:7], off sc1
	s_nop 1
	v_add3_u32 v12, v7, v12, s1
	v_add3_u32 v3, v11, v3, s1
	v_add3_u32 v13, v8, v13, s1
	v_add3_u32 v17, v4, v17, s1
	v_lshrrev_b32_e32 v19, 16, v15
	v_lshrrev_b32_e32 v15, 16, v16
	s_mov_b32 s1, 0xffff0000
	v_pk_mul_f32 v[4:5], v[4:5], v[4:5]
	v_and_or_b32 v15, v3, s1, v15
	v_pk_mul_f32 v[6:7], v[6:7], v[6:7]
	v_add_f32_e32 v3, v4, v5
	v_add_f32_e32 v3, v6, v3
	global_store_dwordx4 v[80:81], v[8:11], off sc1
	s_nop 1
	v_pk_mul_f32 v[8:9], v[8:9], v[8:9]
	v_add_f32_e32 v3, v7, v3
	v_add_f32_e32 v3, v8, v3
	v_lshrrev_b32_e32 v16, 16, v17
	v_lshrrev_b32_e32 v17, 16, v13
	v_pk_mul_f32 v[10:11], v[10:11], v[10:11]
	v_add_f32_e32 v3, v9, v3
	v_and_or_b32 v13, v12, s1, v19
	v_and_or_b32 v14, v14, s1, v17
	v_and_or_b32 v12, v18, s1, v16
	global_store_dwordx4 v[76:77], v[12:15], off sc1
	s_nop 1
	v_add_f32_e32 v3, v10, v3
	v_add_f32_e32 v3, v11, v3
	s_nop 1
	v_mov_b32_dpp v4, v3 quad_perm:[1,0,3,2] row_mask:0xf bank_mask:0xf bound_ctrl:1
	s_and_b64 exec, exec, vcc
	s_cbranch_execz .LBB0_728
	v_lshlrev_b32_e32 v6, 6, v2
	v_ashrrev_i32_e32 v7, 31, v6
	s_ashr_i32 s3, s2, 31
	v_add_f32_e32 v4, v3, v4
	v_lshl_add_u64 v[2:3], v[6:7], 2, s[12:13]
	v_lshl_add_u64 v[2:3], s[2:3], 2, v[2:3]
	global_store_dword v[2:3], v4, off sc1
